# scan phases: waves 0-3 (recurrence) run at s_setprio 3, reset at phase end
# baseline (speedup 1.0000x reference)
; __device__ __forceinline__ int bid_() { int t = blockIdx.x; asm volatile("" : "+s"(t)); return t; }
; __device__ __forceinline__ void scan_phase(const Params& P, float* L, int l) {
;     for (int it = bid_(); it < 224; it += gridDim.x) {
;         if (it < 64) scan_hgrn_mfma(P, (unsigned char*)L, l, it);
;         else if (it < 128) scan_ssd_mfma(P, (unsigned char*)L, l, it - 64);
;         else if (it < 192) scan_ret_mfma(P, (unsigned char*)L, it - 128);
;         else scan_lru(P, L, it - 192);
;     }
; __global__ void __launch_bounds__(512, 2) mk_fwd(Params Pkarg) {
;     ...
;             else if (k == 5) scan_phase(P, L, l);
.LBB0_11:
	s_cmp_eq_u32 s36, 7
	s_cbranch_scc1 .Lsprio_go
	s_cmp_eq_u32 s36, 19
	s_cbranch_scc0 .Lsprio_done
.Lsprio_go:
	v_readfirstlane_b32 s4, v168
	s_cmpk_lt_u32 s4, 0x100
	s_cbranch_scc0 .Lsprio_done
	s_setprio 3

; #define LAS __attribute__((address_space(3)))
; __device__ __forceinline__ unsigned xb_add(unsigned* p, unsigned v) { return __hip_atomic_fetch_add(p, v, __ATOMIC_RELAXED, __HIP_MEMORY_SCOPE_AGENT); }
; __device__ __forceinline__ unsigned xb_xcc_id() { return (unsigned)__builtin_amdgcn_s_getreg((3 << 11) | 20) & 0xFu; }
; __device__ __forceinline__ void xcd_barrier(const XcdBarrier& b) {
;     asm volatile("s_waitcnt vmcnt(0)" ::: "memory");
;     __syncthreads();
;     if (threadIdx.x == 0) {
;         unsigned* bar = b.bar;
;         __builtin_amdgcn_s_waitcnt(0);
;         unsigned nloc = b.st[0], nx = b.st[1];
;         if (nloc == 0u) { xcd_barrier_complete(bar, b.x, nloc, nx); b.st[0] = nloc; b.st[1] = nx; }
;         const unsigned old = xb_add(&bar[XB_XSUB(b.x)], 1u);
; __global__ void __launch_bounds__(512, 2) mk_fwd(Params Pkarg) {
;     ...
;         if (ph + 1 < ph_hi) {
;             if (ph == 0) cg::this_grid().sync();
;             else { XcdBarrier xb; xb.bar = (unsigned*)ws; xb.x = xb_xcc_id(); xb.st = (volatile LAS unsigned*)((LAS unsigned char*)lds_raw + (LDS_BYTES - 128)); xcd_barrier(xb); }
.Lhk_resume:
	s_setprio 0
	s_add_i32 s36, s36, 1
	s_cmp_ge_i32 s36, s37
	s_mov_b64 s[0:1], -1
	s_cbranch_scc1 .LBB0_10
	v_readlane_b32 s0, v254, 52
	v_readlane_b32 s1, v254, 53
	s_and_b64 vcc, exec, s[0:1]
	s_getreg_b32 s4, hwreg(HW_REG_XCC_ID, 0, 4)
	s_waitcnt vmcnt(0)
	s_waitcnt vmcnt(0)
	s_barrier
	s_mov_b64 s[0:1], exec
	v_readlane_b32 s6, v254, 0
	v_readlane_b32 s7, v254, 1
	s_and_b64 s[6:7], s[0:1], s[6:7]
	s_mov_b64 exec, s[6:7]
	s_cbranch_execz .LBB0_626
	v_readlane_b32 s3, v254, 14
	s_waitcnt vmcnt(0) expcnt(0) lgkmcnt(0)
	s_and_b32 s18, s4, 15
	v_mov_b32_e32 v0, s3
	ds_read_b32 v2, v0
	v_readlane_b32 s3, v254, 15
	s_waitcnt lgkmcnt(0)
	v_cmp_ne_u32_e32 vcc, 0, v2
	v_mov_b32_e32 v0, s3
	ds_read_b32 v0, v0
	s_cbranch_vccnz .LBB0_590
	s_load_dwordx2 s[8:9], s[38:39], 0x0
	s_load_dword s7, s[38:39], 0x8
	s_add_u32 s4, s94, 0x1000
	s_addc_u32 s5, s95, 0
	s_add_u32 s6, s94, 0x1100
	s_waitcnt lgkmcnt(0)
	s_mul_i32 s19, s9, s8
	s_mul_i32 s19, s19, s7
	s_addc_u32 s7, s95, 0
	s_add_u32 s8, s94, 0x1200
	s_addc_u32 s9, s95, 0
	s_add_u32 s10, s94, 0x1300
	s_addc_u32 s11, s95, 0
	s_mov_b32 s20, 1
	s_branch .LBB0_577
